# FFN epilogue conv/SiLU multiplies switched to packed f32 (v_pk_fma_f32 / v_pk_mul_f32, same f32 math) to cut VALU issue slots
# speedup vs baseline: 1.0281x; 1.0023x over previous
; __device__ __forceinline__ unsigned cvt_pk_bf16(float lo, float hi) { unsigned r; asm volatile("v_cvt_pk_bf16_f32 %0, %1, %2" : "=v"(r) : "v"(lo), "v"(hi)); return r; }
;     __device__ __forceinline__ void operator()(const f32x4 (&acc)[2][2][4][2], const Unit& u, int wr, int wc, int fr, int fq) const {
;     ...
;                         for (int jj = 0; jj < 4; ++jj) {
;                             const float cur = acc[ai][bj][m][n][jj];
;                             float o1, o2;
;                             if (m > 0) { const float pv = acc[ai][bj][m > 0 ? m - 1 : 0][n][jj]; o1 = dppf<0x121>(0.f, pv); o2 = dppf<0x122>(0.f, pv); }
;                             else { o1 = h15[bj][jj]; o2 = (fr == 0) ? h14[bj][jj] : h15[bj][jj]; }
;                             const float p1 = dppf<0x111>(o1, cur), p2 = dppf<0x112>(o2, cur);
;                             val[bj][jj] = w2[bj][jj] * cur + w1[bj][jj] * p1 + w0[bj][jj] * p2 + bb[bj][jj];
;                         }
;                     float y[4];
; #pragma unroll
;                     for (int jj = 0; jj < 4; ++jj) { const float g = val[1][jj]; y[jj] = val[0][jj] * g * __builtin_amdgcn_rcpf(1.0f + __builtin_amdgcn_exp2f(-1.4426950408889634f * g)); }
;                     u32x2 w; w.x = cvt_pk_bf16(y[0], y[1]); w.y = cvt_pk_bf16(y[2], y[3]);
.Lffn_h00:
	s_waitcnt vmcnt(0) lgkmcnt(0)
	v_mov_b32_dpp v174, v104 row_shr:1 row_mask:0xf bank_mask:0xf
	v_mov_b32_dpp v175, v105 row_shr:1 row_mask:0xf bank_mask:0xf
	v_mov_b32_dpp v176, v106 row_shr:1 row_mask:0xf bank_mask:0xf
	v_mov_b32_dpp v177, v107 row_shr:1 row_mask:0xf bank_mask:0xf
	v_mov_b32_dpp v166, v108 row_shr:1 row_mask:0xf bank_mask:0xf
	v_mov_b32_dpp v167, v109 row_shr:1 row_mask:0xf bank_mask:0xf
	v_mov_b32_dpp v168, v110 row_shr:1 row_mask:0xf bank_mask:0xf
	v_mov_b32_dpp v169, v111 row_shr:1 row_mask:0xf bank_mask:0xf
	v_pk_fma_f32 v[104:105], v[142:143], v[104:105], v[150:151]
	v_pk_fma_f32 v[106:107], v[144:145], v[106:107], v[152:153]
	v_pk_fma_f32 v[104:105], v[134:135], v[108:109], v[104:105]
	v_pk_fma_f32 v[106:107], v[136:137], v[110:111], v[106:107]
	v_pk_fma_f32 v[104:105], v[126:127], v[122:123], v[104:105]
	v_pk_fma_f32 v[106:107], v[128:129], v[124:125], v[106:107]
	v_pk_fma_f32 v[108:109], v[142:143], v[108:109], v[150:151]
	v_pk_fma_f32 v[110:111], v[144:145], v[110:111], v[152:153]
	v_pk_fma_f32 v[108:109], v[134:135], v[122:123], v[108:109]
	v_pk_fma_f32 v[110:111], v[136:137], v[124:125], v[110:111]
	v_pk_fma_f32 v[108:109], v[126:127], v[162:163], v[108:109]
	v_pk_fma_f32 v[110:111], v[128:129], v[164:165], v[110:111]
	v_pk_fma_f32 v[122:123], v[142:143], v[122:123], v[150:151]
	v_pk_fma_f32 v[124:125], v[144:145], v[124:125], v[152:153]
	v_pk_fma_f32 v[122:123], v[134:135], v[162:163], v[122:123]
	v_pk_fma_f32 v[124:125], v[136:137], v[164:165], v[124:125]
	v_pk_fma_f32 v[122:123], v[126:127], v[174:175], v[122:123]
	v_pk_fma_f32 v[124:125], v[128:129], v[176:177], v[124:125]
	v_pk_fma_f32 v[162:163], v[142:143], v[162:163], v[150:151]
	v_pk_fma_f32 v[164:165], v[144:145], v[164:165], v[152:153]
	v_pk_fma_f32 v[162:163], v[134:135], v[174:175], v[162:163]
	v_pk_fma_f32 v[164:165], v[136:137], v[176:177], v[164:165]
	v_pk_fma_f32 v[162:163], v[126:127], v[166:167], v[162:163]
	v_pk_fma_f32 v[164:165], v[128:129], v[168:169], v[164:165]
	v_mov_b32_dpp v118, v96 row_shr:1 row_mask:0xf bank_mask:0xf
	v_mov_b32_dpp v119, v97 row_shr:1 row_mask:0xf bank_mask:0xf
	v_mov_b32_dpp v120, v98 row_shr:1 row_mask:0xf bank_mask:0xf
	v_mov_b32_dpp v121, v99 row_shr:1 row_mask:0xf bank_mask:0xf
	v_mov_b32_dpp v170, v100 row_shr:1 row_mask:0xf bank_mask:0xf
	v_mov_b32_dpp v171, v101 row_shr:1 row_mask:0xf bank_mask:0xf
	v_mov_b32_dpp v172, v102 row_shr:1 row_mask:0xf bank_mask:0xf
	v_mov_b32_dpp v173, v103 row_shr:1 row_mask:0xf bank_mask:0xf
	v_pk_fma_f32 v[96:97], v[146:147], v[96:97], v[154:155]
	v_pk_fma_f32 v[98:99], v[148:149], v[98:99], v[156:157]
	v_pk_fma_f32 v[96:97], v[138:139], v[100:101], v[96:97]
	v_pk_fma_f32 v[98:99], v[140:141], v[102:103], v[98:99]
	v_pk_fma_f32 v[96:97], v[130:131], v[114:115], v[96:97]
	v_pk_fma_f32 v[98:99], v[132:133], v[116:117], v[98:99]
	v_pk_fma_f32 v[100:101], v[146:147], v[100:101], v[154:155]
	v_pk_fma_f32 v[102:103], v[148:149], v[102:103], v[156:157]
	v_pk_fma_f32 v[100:101], v[138:139], v[114:115], v[100:101]
	v_pk_fma_f32 v[102:103], v[140:141], v[116:117], v[102:103]
	v_pk_fma_f32 v[100:101], v[130:131], v[158:159], v[100:101]
	v_pk_fma_f32 v[102:103], v[132:133], v[160:161], v[102:103]
	v_pk_fma_f32 v[114:115], v[146:147], v[114:115], v[154:155]
	v_pk_fma_f32 v[116:117], v[148:149], v[116:117], v[156:157]
	v_pk_fma_f32 v[114:115], v[138:139], v[158:159], v[114:115]
	v_pk_fma_f32 v[116:117], v[140:141], v[160:161], v[116:117]
	v_pk_fma_f32 v[114:115], v[130:131], v[118:119], v[114:115]
	v_pk_fma_f32 v[116:117], v[132:133], v[120:121], v[116:117]
	v_pk_fma_f32 v[158:159], v[146:147], v[158:159], v[154:155]
	v_pk_fma_f32 v[160:161], v[148:149], v[160:161], v[156:157]
	v_pk_fma_f32 v[158:159], v[138:139], v[118:119], v[158:159]
	v_pk_fma_f32 v[160:161], v[140:141], v[120:121], v[160:161]
	v_pk_fma_f32 v[158:159], v[130:131], v[170:171], v[158:159]
	v_pk_fma_f32 v[160:161], v[132:133], v[172:173], v[160:161]
	v_mul_f32_e32 v208, s71, v158
	v_mul_f32_e32 v209, s71, v159
	v_mul_f32_e32 v210, s71, v160
	v_mul_f32_e32 v211, s71, v161
	v_exp_f32_e32 v208, v208
	v_exp_f32_e32 v209, v209
	v_exp_f32_e32 v210, v210
	v_exp_f32_e32 v211, v211
	v_pk_mul_f32 v[162:163], v[162:163], v[158:159]
	v_pk_mul_f32 v[164:165], v[164:165], v[160:161]
	v_add_f32_e32 v208, 1.0, v208
	v_add_f32_e32 v209, 1.0, v209
	v_add_f32_e32 v210, 1.0, v210
	v_add_f32_e32 v211, 1.0, v211
	v_rcp_f32_e32 v208, v208
	v_rcp_f32_e32 v209, v209
	v_rcp_f32_e32 v210, v210
	v_rcp_f32_e32 v211, v211
	s_nop 0
	v_pk_mul_f32 v[162:163], v[162:163], v[208:209]
	v_pk_mul_f32 v[164:165], v[164:165], v[210:211]
	v_cvt_pk_bf16_f32 v158, v162, v163
	v_cvt_pk_bf16_f32 v159, v164, v165
	v_mul_f32_e32 v208, s71, v114
	v_mul_f32_e32 v209, s71, v115
	v_mul_f32_e32 v210, s71, v116
	v_mul_f32_e32 v211, s71, v117
	v_exp_f32_e32 v208, v208
	v_exp_f32_e32 v209, v209
	v_exp_f32_e32 v210, v210
	v_exp_f32_e32 v211, v211
	v_pk_mul_f32 v[122:123], v[122:123], v[114:115]
	v_pk_mul_f32 v[124:125], v[124:125], v[116:117]
	v_add_f32_e32 v208, 1.0, v208
	v_add_f32_e32 v209, 1.0, v209
	v_add_f32_e32 v210, 1.0, v210
	v_add_f32_e32 v211, 1.0, v211
	v_rcp_f32_e32 v208, v208
	v_rcp_f32_e32 v209, v209
	v_rcp_f32_e32 v210, v210
	v_rcp_f32_e32 v211, v211
	s_nop 0
	v_pk_mul_f32 v[122:123], v[122:123], v[208:209]
	v_pk_mul_f32 v[124:125], v[124:125], v[210:211]
	v_cvt_pk_bf16_f32 v114, v122, v123
	v_cvt_pk_bf16_f32 v115, v124, v125
	v_mul_f32_e32 v208, s71, v100
	v_mul_f32_e32 v209, s71, v101
	v_mul_f32_e32 v210, s71, v102
	v_mul_f32_e32 v211, s71, v103
	v_exp_f32_e32 v208, v208
	v_exp_f32_e32 v209, v209
	v_exp_f32_e32 v210, v210
	v_exp_f32_e32 v211, v211
	v_pk_mul_f32 v[108:109], v[108:109], v[100:101]
	v_pk_mul_f32 v[110:111], v[110:111], v[102:103]
	v_add_f32_e32 v208, 1.0, v208
	v_add_f32_e32 v209, 1.0, v209
	v_add_f32_e32 v210, 1.0, v210
	v_add_f32_e32 v211, 1.0, v211
	v_rcp_f32_e32 v208, v208
	v_rcp_f32_e32 v209, v209
	v_rcp_f32_e32 v210, v210
	v_rcp_f32_e32 v211, v211
	s_nop 0
	v_pk_mul_f32 v[108:109], v[108:109], v[208:209]
	v_pk_mul_f32 v[110:111], v[110:111], v[210:211]
	v_cvt_pk_bf16_f32 v100, v108, v109
	v_cvt_pk_bf16_f32 v101, v110, v111
	v_mul_f32_e32 v208, s71, v96
	v_mul_f32_e32 v209, s71, v97
	v_mul_f32_e32 v210, s71, v98
	v_mul_f32_e32 v211, s71, v99
	v_exp_f32_e32 v208, v208
	v_exp_f32_e32 v209, v209
	v_exp_f32_e32 v210, v210
	v_exp_f32_e32 v211, v211
	v_pk_mul_f32 v[104:105], v[104:105], v[96:97]
	v_pk_mul_f32 v[106:107], v[106:107], v[98:99]
	v_add_f32_e32 v208, 1.0, v208
	v_add_f32_e32 v209, 1.0, v209
	v_add_f32_e32 v210, 1.0, v210
	v_add_f32_e32 v211, 1.0, v211
	v_rcp_f32_e32 v208, v208
	v_rcp_f32_e32 v209, v209
	v_rcp_f32_e32 v210, v210
	v_rcp_f32_e32 v211, v211
	s_nop 0
	v_pk_mul_f32 v[104:105], v[104:105], v[208:209]
	v_pk_mul_f32 v[106:107], v[106:107], v[210:211]
	v_cvt_pk_bf16_f32 v96, v104, v105
	v_cvt_pk_bf16_f32 v97, v106, v107
	s_mov_b32 s1, 0x800
	s_and_b64 vcc, exec, s[36:37]
	s_cbranch_vccz .Lffn_hs
	s_mov_b32 s1, 0x1000
; #define PG8_LAS __attribute__((address_space(3)))
; __device__ __forceinline__ unsigned cvt_pk_bf16(float lo, float hi) { unsigned r; asm volatile("v_cvt_pk_bf16_f32 %0, %1, %2" : "=v"(r) : "v"(lo), "v"(hi)); return r; }
;     __device__ __forceinline__ void operator()(const f32x4 (&acc)[2][2][4][2], const Unit& u, int wr, int wc, int fr, int fq) const {
;     ...
;                 if (wr == 1 || ai == 1) { const int src = (wr == 1) ? (ai * 2 + 0) : (0 * 2 + 1);
; #pragma unroll
;                     for (int bj = 0; bj < 2; ++bj) { h14[bj] = *(const PG8_LAS f32x4*)(xch + (src * 4 + wc) * 128 + 0 * 64 + (bj * 2 + n) * 16 + fq * 4); h15[bj] = *(const PG8_LAS f32x4*)(xch + (src * 4 + wc) * 128 + 1 * 64 + (bj * 2 + n) * 16 + fq * 4); }
;                 } else {
; #pragma unroll
;                     for (int bj = 0; bj < 2; ++bj) { h14[bj] = (f32x4){0.f, 0.f, 0.f, 0.f}; h15[bj] = (f32x4){0.f, 0.f, 0.f, 0.f}; } }
; #pragma unroll
;                 for (int m = 0; m < 4; ++m) {
;                     float val[2][4];
; #pragma unroll
;                     for (int bj = 0; bj < 2; ++bj)
; #pragma unroll
;                         for (int jj = 0; jj < 4; ++jj) {
;                             const float cur = acc[ai][bj][m][n][jj];
;                             float o1, o2;
;                             if (m > 0) { const float pv = acc[ai][bj][m > 0 ? m - 1 : 0][n][jj]; o1 = dppf<0x121>(0.f, pv); o2 = dppf<0x122>(0.f, pv); }
;                             else { o1 = h15[bj][jj]; o2 = (fr == 0) ? h14[bj][jj] : h15[bj][jj]; }
;                             const float p1 = dppf<0x111>(o1, cur), p2 = dppf<0x112>(o2, cur);
;                             val[bj][jj] = w2[bj][jj] * cur + w1[bj][jj] * p1 + w0[bj][jj] * p2 + bb[bj][jj];
;                         }
;                     float y[4];
; #pragma unroll
;                     for (int jj = 0; jj < 4; ++jj) { const float g = val[1][jj]; y[jj] = val[0][jj] * g * __builtin_amdgcn_rcpf(1.0f + __builtin_amdgcn_exp2f(-1.4426950408889634f * g)); }
;                     u32x2 w; w.x = cvt_pk_bf16(y[0], y[1]); w.y = cvt_pk_bf16(y[2], y[3]);
.Lffn_hs:
	v_add_u32_e32 v206, s1, v214
	ds_read_b128 v[166:169], v206
	ds_read_b128 v[174:177], v206 offset:256
	ds_read_b128 v[170:173], v206 offset:128
	ds_read_b128 v[118:121], v206 offset:384
	s_waitcnt lgkmcnt(0)
	v_mov_b32_dpp v174, v72 row_shr:1 row_mask:0xf bank_mask:0xf
	v_mov_b32_dpp v175, v73 row_shr:1 row_mask:0xf bank_mask:0xf
	v_mov_b32_dpp v176, v74 row_shr:1 row_mask:0xf bank_mask:0xf
	v_mov_b32_dpp v177, v75 row_shr:1 row_mask:0xf bank_mask:0xf
	v_mov_b32_dpp v166, v76 row_shr:1 row_mask:0xf bank_mask:0xf
	v_mov_b32_dpp v167, v77 row_shr:1 row_mask:0xf bank_mask:0xf
	v_mov_b32_dpp v168, v78 row_shr:1 row_mask:0xf bank_mask:0xf
	v_mov_b32_dpp v169, v79 row_shr:1 row_mask:0xf bank_mask:0xf
	v_pk_fma_f32 v[72:73], v[142:143], v[72:73], v[150:151]
	v_pk_fma_f32 v[74:75], v[144:145], v[74:75], v[152:153]
	v_pk_fma_f32 v[72:73], v[134:135], v[76:77], v[72:73]
	v_pk_fma_f32 v[74:75], v[136:137], v[78:79], v[74:75]
	v_pk_fma_f32 v[72:73], v[126:127], v[84:85], v[72:73]
	v_pk_fma_f32 v[74:75], v[128:129], v[86:87], v[74:75]
	v_pk_fma_f32 v[76:77], v[142:143], v[76:77], v[150:151]
	v_pk_fma_f32 v[78:79], v[144:145], v[78:79], v[152:153]
	v_pk_fma_f32 v[76:77], v[134:135], v[84:85], v[76:77]
	v_pk_fma_f32 v[78:79], v[136:137], v[86:87], v[78:79]
	v_pk_fma_f32 v[76:77], v[126:127], v[92:93], v[76:77]
	v_pk_fma_f32 v[78:79], v[128:129], v[94:95], v[78:79]
	v_pk_fma_f32 v[84:85], v[142:143], v[84:85], v[150:151]
	v_pk_fma_f32 v[86:87], v[144:145], v[86:87], v[152:153]
	v_pk_fma_f32 v[84:85], v[134:135], v[92:93], v[84:85]
	v_pk_fma_f32 v[86:87], v[136:137], v[94:95], v[86:87]
	v_pk_fma_f32 v[84:85], v[126:127], v[174:175], v[84:85]
	v_pk_fma_f32 v[86:87], v[128:129], v[176:177], v[86:87]
	v_pk_fma_f32 v[92:93], v[142:143], v[92:93], v[150:151]
	v_pk_fma_f32 v[94:95], v[144:145], v[94:95], v[152:153]
	v_pk_fma_f32 v[92:93], v[134:135], v[174:175], v[92:93]
	v_pk_fma_f32 v[94:95], v[136:137], v[176:177], v[94:95]
	v_pk_fma_f32 v[92:93], v[126:127], v[166:167], v[92:93]
	v_pk_fma_f32 v[94:95], v[128:129], v[168:169], v[94:95]
	v_mov_b32_dpp v118, v64 row_shr:1 row_mask:0xf bank_mask:0xf
	v_mov_b32_dpp v119, v65 row_shr:1 row_mask:0xf bank_mask:0xf
	v_mov_b32_dpp v120, v66 row_shr:1 row_mask:0xf bank_mask:0xf
	v_mov_b32_dpp v121, v67 row_shr:1 row_mask:0xf bank_mask:0xf
	v_mov_b32_dpp v170, v68 row_shr:1 row_mask:0xf bank_mask:0xf
	v_mov_b32_dpp v171, v69 row_shr:1 row_mask:0xf bank_mask:0xf
	v_mov_b32_dpp v172, v70 row_shr:1 row_mask:0xf bank_mask:0xf
	v_mov_b32_dpp v173, v71 row_shr:1 row_mask:0xf bank_mask:0xf
	v_pk_fma_f32 v[64:65], v[146:147], v[64:65], v[154:155]
	v_pk_fma_f32 v[66:67], v[148:149], v[66:67], v[156:157]
	v_pk_fma_f32 v[64:65], v[138:139], v[68:69], v[64:65]
	v_pk_fma_f32 v[66:67], v[140:141], v[70:71], v[66:67]
	v_pk_fma_f32 v[64:65], v[130:131], v[80:81], v[64:65]
	v_pk_fma_f32 v[66:67], v[132:133], v[82:83], v[66:67]
	v_pk_fma_f32 v[68:69], v[146:147], v[68:69], v[154:155]
	v_pk_fma_f32 v[70:71], v[148:149], v[70:71], v[156:157]
	v_pk_fma_f32 v[68:69], v[138:139], v[80:81], v[68:69]
	v_pk_fma_f32 v[70:71], v[140:141], v[82:83], v[70:71]
	v_pk_fma_f32 v[68:69], v[130:131], v[88:89], v[68:69]
	v_pk_fma_f32 v[70:71], v[132:133], v[90:91], v[70:71]
	v_pk_fma_f32 v[80:81], v[146:147], v[80:81], v[154:155]
	v_pk_fma_f32 v[82:83], v[148:149], v[82:83], v[156:157]
	v_pk_fma_f32 v[80:81], v[138:139], v[88:89], v[80:81]
	v_pk_fma_f32 v[82:83], v[140:141], v[90:91], v[82:83]
	v_pk_fma_f32 v[80:81], v[130:131], v[118:119], v[80:81]
	v_pk_fma_f32 v[82:83], v[132:133], v[120:121], v[82:83]
	v_pk_fma_f32 v[88:89], v[146:147], v[88:89], v[154:155]
	v_pk_fma_f32 v[90:91], v[148:149], v[90:91], v[156:157]
	v_pk_fma_f32 v[88:89], v[138:139], v[118:119], v[88:89]
	v_pk_fma_f32 v[90:91], v[140:141], v[120:121], v[90:91]
	v_pk_fma_f32 v[88:89], v[130:131], v[170:171], v[88:89]
	v_pk_fma_f32 v[90:91], v[132:133], v[172:173], v[90:91]
	v_mul_f32_e32 v208, s71, v88
	v_mul_f32_e32 v209, s71, v89
	v_mul_f32_e32 v210, s71, v90
	v_mul_f32_e32 v211, s71, v91
	v_exp_f32_e32 v208, v208
	v_exp_f32_e32 v209, v209
	v_exp_f32_e32 v210, v210
	v_exp_f32_e32 v211, v211
	v_pk_mul_f32 v[92:93], v[92:93], v[88:89]
	v_pk_mul_f32 v[94:95], v[94:95], v[90:91]
	v_add_f32_e32 v208, 1.0, v208
	v_add_f32_e32 v209, 1.0, v209
	v_add_f32_e32 v210, 1.0, v210
	v_add_f32_e32 v211, 1.0, v211
	v_rcp_f32_e32 v208, v208
	v_rcp_f32_e32 v209, v209
	v_rcp_f32_e32 v210, v210
	v_rcp_f32_e32 v211, v211
	s_nop 0
	v_pk_mul_f32 v[92:93], v[92:93], v[208:209]
	v_pk_mul_f32 v[94:95], v[94:95], v[210:211]
	v_cvt_pk_bf16_f32 v88, v92, v93
	v_cvt_pk_bf16_f32 v89, v94, v95
	v_mul_f32_e32 v208, s71, v80
	v_mul_f32_e32 v209, s71, v81
	v_mul_f32_e32 v210, s71, v82
	v_mul_f32_e32 v211, s71, v83
	v_exp_f32_e32 v208, v208
	v_exp_f32_e32 v209, v209
	v_exp_f32_e32 v210, v210
	v_exp_f32_e32 v211, v211
	v_pk_mul_f32 v[84:85], v[84:85], v[80:81]
	v_pk_mul_f32 v[86:87], v[86:87], v[82:83]
	v_add_f32_e32 v208, 1.0, v208
	v_add_f32_e32 v209, 1.0, v209
	v_add_f32_e32 v210, 1.0, v210
	v_add_f32_e32 v211, 1.0, v211
	v_rcp_f32_e32 v208, v208
	v_rcp_f32_e32 v209, v209
	v_rcp_f32_e32 v210, v210
	v_rcp_f32_e32 v211, v211
	s_nop 0
	v_pk_mul_f32 v[84:85], v[84:85], v[208:209]
	v_pk_mul_f32 v[86:87], v[86:87], v[210:211]
	v_cvt_pk_bf16_f32 v80, v84, v85
	v_cvt_pk_bf16_f32 v81, v86, v87
	v_mul_f32_e32 v208, s71, v68
	v_mul_f32_e32 v209, s71, v69
	v_mul_f32_e32 v210, s71, v70
	v_mul_f32_e32 v211, s71, v71
	v_exp_f32_e32 v208, v208
	v_exp_f32_e32 v209, v209
	v_exp_f32_e32 v210, v210
	v_exp_f32_e32 v211, v211
	v_pk_mul_f32 v[76:77], v[76:77], v[68:69]
	v_pk_mul_f32 v[78:79], v[78:79], v[70:71]
	v_add_f32_e32 v208, 1.0, v208
; #define PG8_LAS __attribute__((address_space(3)))
;     __device__ __forceinline__ void operator()(const f32x4 (&acc)[2][2][4][2], const Unit& u, int wr, int wc, int fr, int fq) const {
;     ...
;             for (int bj = 0; bj < 2; ++bj) { w0[bj] = *(const f32x4*)(cw + bj * dff + ch0); w1[bj] = *(const f32x4*)(cw + upw + bj * dff + ch0); w2[bj] = *(const f32x4*)(cw + 2 * upw + bj * dff + ch0); bb[bj] = *(const f32x4*)(cb + bj * dff + ch0); }
; #pragma unroll
;             for (int ai = 0; ai < 2; ++ai) {
;                 f32x4 h15[2], h14[2];
;                 if (wr == 1 || ai == 1) { const int src = (wr == 1) ? (ai * 2 + 0) : (0 * 2 + 1);
; #pragma unroll
;                     for (int bj = 0; bj < 2; ++bj) { h14[bj] = *(const PG8_LAS f32x4*)(xch + (src * 4 + wc) * 128 + 0 * 64 + (bj * 2 + n) * 16 + fq * 4); h15[bj] = *(const PG8_LAS f32x4*)(xch + (src * 4 + wc) * 128 + 1 * 64 + (bj * 2 + n) * 16 + fq * 4); }
;                 } else {
; #pragma unroll
;                     for (int bj = 0; bj < 2; ++bj) { h14[bj] = (f32x4){0.f, 0.f, 0.f, 0.f}; h15[bj] = (f32x4){0.f, 0.f, 0.f, 0.f}; } }
; #pragma unroll
;                 for (int m = 0; m < 4; ++m) {
;                     float val[2][4];
; #pragma unroll
;                     for (int bj = 0; bj < 2; ++bj)
; #pragma unroll
;                         for (int jj = 0; jj < 4; ++jj) {
;                             const float cur = acc[ai][bj][m][n][jj];
;                             float o1, o2;
;                             if (m > 0) { const float pv = acc[ai][bj][m > 0 ? m - 1 : 0][n][jj]; o1 = dppf<0x121>(0.f, pv); o2 = dppf<0x122>(0.f, pv); }
;                             else { o1 = h15[bj][jj]; o2 = (fr == 0) ? h14[bj][jj] : h15[bj][jj]; }
;                             const float p1 = dppf<0x111>(o1, cur), p2 = dppf<0x112>(o2, cur);
;                             val[bj][jj] = w2[bj][jj] * cur + w1[bj][jj] * p1 + w0[bj][jj] * p2 + bb[bj][jj];
;                         }
;                     float y[4];
; #pragma unroll
;                     for (int jj = 0; jj < 4; ++jj) { const float g = val[1][jj]; y[jj] = val[0][jj] * g * __builtin_amdgcn_rcpf(1.0f + __builtin_amdgcn_exp2f(-1.4426950408889634f * g)); }
;                     u32x2 w; w.x = cvt_pk_bf16(y[0], y[1]); w.y = cvt_pk_bf16(y[2], y[3]);
	v_add_f32_e32 v209, 1.0, v209
	v_add_f32_e32 v210, 1.0, v210
	v_add_f32_e32 v211, 1.0, v211
	v_rcp_f32_e32 v208, v208
	v_rcp_f32_e32 v209, v209
	v_rcp_f32_e32 v210, v210
	v_rcp_f32_e32 v211, v211
	s_nop 0
	v_pk_mul_f32 v[76:77], v[76:77], v[208:209]
	v_pk_mul_f32 v[78:79], v[78:79], v[210:211]
	v_cvt_pk_bf16_f32 v68, v76, v77
	v_cvt_pk_bf16_f32 v69, v78, v79
	v_mul_f32_e32 v208, s71, v64
	v_mul_f32_e32 v209, s71, v65
	v_mul_f32_e32 v210, s71, v66
	v_mul_f32_e32 v211, s71, v67
	v_exp_f32_e32 v208, v208
	v_exp_f32_e32 v209, v209
	v_exp_f32_e32 v210, v210
	v_exp_f32_e32 v211, v211
	v_pk_mul_f32 v[72:73], v[72:73], v[64:65]
	v_pk_mul_f32 v[74:75], v[74:75], v[66:67]
	v_add_f32_e32 v208, 1.0, v208
	v_add_f32_e32 v209, 1.0, v209
	v_add_f32_e32 v210, 1.0, v210
	v_add_f32_e32 v211, 1.0, v211
	v_rcp_f32_e32 v208, v208
	v_rcp_f32_e32 v209, v209
	v_rcp_f32_e32 v210, v210
	v_rcp_f32_e32 v211, v211
	s_nop 0
	v_pk_mul_f32 v[72:73], v[72:73], v[208:209]
	v_pk_mul_f32 v[74:75], v[74:75], v[210:211]
	v_cvt_pk_bf16_f32 v64, v72, v73
	v_cvt_pk_bf16_f32 v65, v74, v75
	global_load_dwordx4 v[126:129], v112, s[26:27] offset:16
	global_load_dwordx4 v[130:133], v113, s[26:27] offset:16
	global_load_dwordx4 v[134:137], v112, s[58:59] offset:16
	global_load_dwordx4 v[138:141], v113, s[58:59] offset:16
	global_load_dwordx4 v[142:145], v112, s[60:61] offset:16
	global_load_dwordx4 v[146:149], v113, s[60:61] offset:16
	global_load_dwordx4 v[150:153], v112, s[44:45] offset:16
	global_load_dwordx4 v[154:157], v113, s[44:45] offset:16
	v_mov_b32_e32 v166, 0
	v_mov_b32_e32 v174, 0
	v_mov_b32_e32 v167, 0
	v_mov_b32_e32 v175, 0
	v_mov_b32_e32 v168, 0
	v_mov_b32_e32 v176, 0
	v_mov_b32_e32 v169, 0
	v_mov_b32_e32 v177, 0
	v_mov_b32_e32 v170, 0
	v_mov_b32_e32 v118, 0
	v_mov_b32_e32 v171, 0
	v_mov_b32_e32 v119, 0
	v_mov_b32_e32 v172, 0
	v_mov_b32_e32 v120, 0
	v_mov_b32_e32 v173, 0
	v_mov_b32_e32 v121, 0
	s_and_b64 vcc, exec, s[36:37]
	s_cbranch_vccz .Lffn_h10
	ds_read_b128 v[166:169], v214 offset:64
	ds_read_b128 v[174:177], v214 offset:320
	ds_read_b128 v[170:173], v214 offset:192
	ds_read_b128 v[118:121], v214 offset:448
.Lffn_h10:
	s_waitcnt vmcnt(0) lgkmcnt(0)
	v_mov_b32_dpp v174, v40 row_shr:1 row_mask:0xf bank_mask:0xf
	v_mov_b32_dpp v175, v41 row_shr:1 row_mask:0xf bank_mask:0xf
	v_mov_b32_dpp v176, v42 row_shr:1 row_mask:0xf bank_mask:0xf
	v_mov_b32_dpp v177, v43 row_shr:1 row_mask:0xf bank_mask:0xf
	v_mov_b32_dpp v166, v44 row_shr:1 row_mask:0xf bank_mask:0xf
	v_mov_b32_dpp v167, v45 row_shr:1 row_mask:0xf bank_mask:0xf
	v_mov_b32_dpp v168, v46 row_shr:1 row_mask:0xf bank_mask:0xf
	v_mov_b32_dpp v169, v47 row_shr:1 row_mask:0xf bank_mask:0xf
	v_pk_fma_f32 v[40:41], v[142:143], v[40:41], v[150:151]
	v_pk_fma_f32 v[42:43], v[144:145], v[42:43], v[152:153]
	v_pk_fma_f32 v[40:41], v[134:135], v[44:45], v[40:41]
	v_pk_fma_f32 v[42:43], v[136:137], v[46:47], v[42:43]
	v_pk_fma_f32 v[40:41], v[126:127], v[52:53], v[40:41]
	v_pk_fma_f32 v[42:43], v[128:129], v[54:55], v[42:43]
	v_pk_fma_f32 v[44:45], v[142:143], v[44:45], v[150:151]
	v_pk_fma_f32 v[46:47], v[144:145], v[46:47], v[152:153]
	v_pk_fma_f32 v[44:45], v[134:135], v[52:53], v[44:45]
	v_pk_fma_f32 v[46:47], v[136:137], v[54:55], v[46:47]
	v_pk_fma_f32 v[44:45], v[126:127], v[60:61], v[44:45]
	v_pk_fma_f32 v[46:47], v[128:129], v[62:63], v[46:47]
	v_pk_fma_f32 v[52:53], v[142:143], v[52:53], v[150:151]
	v_pk_fma_f32 v[54:55], v[144:145], v[54:55], v[152:153]
	v_pk_fma_f32 v[52:53], v[134:135], v[60:61], v[52:53]
	v_pk_fma_f32 v[54:55], v[136:137], v[62:63], v[54:55]
	v_pk_fma_f32 v[52:53], v[126:127], v[174:175], v[52:53]
	v_pk_fma_f32 v[54:55], v[128:129], v[176:177], v[54:55]
	v_pk_fma_f32 v[60:61], v[142:143], v[60:61], v[150:151]
	v_pk_fma_f32 v[62:63], v[144:145], v[62:63], v[152:153]
	v_pk_fma_f32 v[60:61], v[134:135], v[174:175], v[60:61]
	v_pk_fma_f32 v[62:63], v[136:137], v[176:177], v[62:63]
	v_pk_fma_f32 v[60:61], v[126:127], v[166:167], v[60:61]
	v_pk_fma_f32 v[62:63], v[128:129], v[168:169], v[62:63]
	v_mov_b32_dpp v118, v32 row_shr:1 row_mask:0xf bank_mask:0xf
	v_mov_b32_dpp v119, v33 row_shr:1 row_mask:0xf bank_mask:0xf
	v_mov_b32_dpp v120, v34 row_shr:1 row_mask:0xf bank_mask:0xf
	v_mov_b32_dpp v121, v35 row_shr:1 row_mask:0xf bank_mask:0xf
	v_mov_b32_dpp v170, v36 row_shr:1 row_mask:0xf bank_mask:0xf
	v_mov_b32_dpp v171, v37 row_shr:1 row_mask:0xf bank_mask:0xf
	v_mov_b32_dpp v172, v38 row_shr:1 row_mask:0xf bank_mask:0xf
	v_mov_b32_dpp v173, v39 row_shr:1 row_mask:0xf bank_mask:0xf
	v_pk_fma_f32 v[32:33], v[146:147], v[32:33], v[154:155]
	v_pk_fma_f32 v[34:35], v[148:149], v[34:35], v[156:157]
	v_pk_fma_f32 v[32:33], v[138:139], v[36:37], v[32:33]
	v_pk_fma_f32 v[34:35], v[140:141], v[38:39], v[34:35]
	v_pk_fma_f32 v[32:33], v[130:131], v[48:49], v[32:33]
	v_pk_fma_f32 v[34:35], v[132:133], v[50:51], v[34:35]
	v_pk_fma_f32 v[36:37], v[146:147], v[36:37], v[154:155]
	v_pk_fma_f32 v[38:39], v[148:149], v[38:39], v[156:157]
	v_pk_fma_f32 v[36:37], v[138:139], v[48:49], v[36:37]
	v_pk_fma_f32 v[38:39], v[140:141], v[50:51], v[38:39]
	v_pk_fma_f32 v[36:37], v[130:131], v[56:57], v[36:37]
	v_pk_fma_f32 v[38:39], v[132:133], v[58:59], v[38:39]
	v_pk_fma_f32 v[48:49], v[146:147], v[48:49], v[154:155]
	v_pk_fma_f32 v[50:51], v[148:149], v[50:51], v[156:157]
	v_pk_fma_f32 v[48:49], v[138:139], v[56:57], v[48:49]
	v_pk_fma_f32 v[50:51], v[140:141], v[58:59], v[50:51]
	v_pk_fma_f32 v[48:49], v[130:131], v[118:119], v[48:49]
	v_pk_fma_f32 v[50:51], v[132:133], v[120:121], v[50:51]
	v_pk_fma_f32 v[56:57], v[146:147], v[56:57], v[154:155]
	v_pk_fma_f32 v[58:59], v[148:149], v[58:59], v[156:157]
; __device__ __forceinline__ unsigned cvt_pk_bf16(float lo, float hi) { unsigned r; asm volatile("v_cvt_pk_bf16_f32 %0, %1, %2" : "=v"(r) : "v"(lo), "v"(hi)); return r; }
;     __device__ __forceinline__ void operator()(const f32x4 (&acc)[2][2][4][2], const Unit& u, int wr, int wc, int fr, int fq) const {
;     ...
;                             val[bj][jj] = w2[bj][jj] * cur + w1[bj][jj] * p1 + w0[bj][jj] * p2 + bb[bj][jj];
;                         }
;                     float y[4];
; #pragma unroll
;                     for (int jj = 0; jj < 4; ++jj) { const float g = val[1][jj]; y[jj] = val[0][jj] * g * __builtin_amdgcn_rcpf(1.0f + __builtin_amdgcn_exp2f(-1.4426950408889634f * g)); }
;                     u32x2 w; w.x = cvt_pk_bf16(y[0], y[1]); w.y = cvt_pk_bf16(y[2], y[3]);
;                     if (n == 0) keep[ai][m] = w;
;                     else { const int row = u.pm * BM + ai * HALF + wr * 64 + m * 16 + fr;
;                         u32x4 w4; w4.x = keep[ai][m].x; w4.y = keep[ai][m].y; w4.z = w.x; w4.w = w.y;
;                         *(u32x4*)(act + (size_t)row * dff + ch0 - 4) = w4; }
	v_pk_fma_f32 v[56:57], v[138:139], v[118:119], v[56:57]
	v_pk_fma_f32 v[58:59], v[140:141], v[120:121], v[58:59]
	v_pk_fma_f32 v[56:57], v[130:131], v[170:171], v[56:57]
	v_pk_fma_f32 v[58:59], v[132:133], v[172:173], v[58:59]
	v_mul_f32_e32 v208, s71, v56
	v_mul_f32_e32 v209, s71, v57
	v_mul_f32_e32 v210, s71, v58
	v_mul_f32_e32 v211, s71, v59
	v_exp_f32_e32 v208, v208
	v_exp_f32_e32 v209, v209
	v_exp_f32_e32 v210, v210
	v_exp_f32_e32 v211, v211
	v_pk_mul_f32 v[60:61], v[60:61], v[56:57]
	v_pk_mul_f32 v[62:63], v[62:63], v[58:59]
	v_add_f32_e32 v208, 1.0, v208
	v_add_f32_e32 v209, 1.0, v209
	v_add_f32_e32 v210, 1.0, v210
	v_add_f32_e32 v211, 1.0, v211
	v_rcp_f32_e32 v208, v208
	v_rcp_f32_e32 v209, v209
	v_rcp_f32_e32 v210, v210
	v_rcp_f32_e32 v211, v211
	s_nop 0
	v_pk_mul_f32 v[60:61], v[60:61], v[208:209]
	v_pk_mul_f32 v[62:63], v[62:63], v[210:211]
	v_cvt_pk_bf16_f32 v160, v60, v61
	v_cvt_pk_bf16_f32 v161, v62, v63
	global_store_dwordx4 v188, v[158:161], s[30:31]
	s_add_u32 s30, s30, 0x2c00
	s_addc_u32 s31, s31, 0
	v_mul_f32_e32 v208, s71, v48
	v_mul_f32_e32 v209, s71, v49
	v_mul_f32_e32 v210, s71, v50
	v_mul_f32_e32 v211, s71, v51
	v_exp_f32_e32 v208, v208
	v_exp_f32_e32 v209, v209
	v_exp_f32_e32 v210, v210
	v_exp_f32_e32 v211, v211
	v_pk_mul_f32 v[52:53], v[52:53], v[48:49]
	v_pk_mul_f32 v[54:55], v[54:55], v[50:51]
	v_add_f32_e32 v208, 1.0, v208
	v_add_f32_e32 v209, 1.0, v209
	v_add_f32_e32 v210, 1.0, v210
	v_add_f32_e32 v211, 1.0, v211
	v_rcp_f32_e32 v208, v208
	v_rcp_f32_e32 v209, v209
	v_rcp_f32_e32 v210, v210
	v_rcp_f32_e32 v211, v211
	s_nop 0
	v_pk_mul_f32 v[52:53], v[52:53], v[208:209]
	v_pk_mul_f32 v[54:55], v[54:55], v[210:211]
	v_cvt_pk_bf16_f32 v116, v52, v53
	v_cvt_pk_bf16_f32 v117, v54, v55
	global_store_dwordx4 v188, v[114:117], s[30:31]
	s_add_u32 s30, s30, 0x2c00
	s_addc_u32 s31, s31, 0
	v_mul_f32_e32 v208, s71, v36
	v_mul_f32_e32 v209, s71, v37
	v_mul_f32_e32 v210, s71, v38
	v_mul_f32_e32 v211, s71, v39
	v_exp_f32_e32 v208, v208
	v_exp_f32_e32 v209, v209
	v_exp_f32_e32 v210, v210
	v_exp_f32_e32 v211, v211
	v_pk_mul_f32 v[44:45], v[44:45], v[36:37]
	v_pk_mul_f32 v[46:47], v[46:47], v[38:39]
	v_add_f32_e32 v208, 1.0, v208
	v_add_f32_e32 v209, 1.0, v209
	v_add_f32_e32 v210, 1.0, v210
	v_add_f32_e32 v211, 1.0, v211
	v_rcp_f32_e32 v208, v208
	v_rcp_f32_e32 v209, v209
	v_rcp_f32_e32 v210, v210
	v_rcp_f32_e32 v211, v211
	s_nop 0
	v_pk_mul_f32 v[44:45], v[44:45], v[208:209]
	v_pk_mul_f32 v[46:47], v[46:47], v[210:211]
	v_cvt_pk_bf16_f32 v102, v44, v45
	v_cvt_pk_bf16_f32 v103, v46, v47
	global_store_dwordx4 v188, v[100:103], s[30:31]
	s_add_u32 s30, s30, 0x2c00
	s_addc_u32 s31, s31, 0
	v_mul_f32_e32 v208, s71, v32
	v_mul_f32_e32 v209, s71, v33
	v_mul_f32_e32 v210, s71, v34
	v_mul_f32_e32 v211, s71, v35
	v_exp_f32_e32 v208, v208
	v_exp_f32_e32 v209, v209
	v_exp_f32_e32 v210, v210
	v_exp_f32_e32 v211, v211
	v_pk_mul_f32 v[40:41], v[40:41], v[32:33]
	v_pk_mul_f32 v[42:43], v[42:43], v[34:35]
	v_add_f32_e32 v208, 1.0, v208
	v_add_f32_e32 v209, 1.0, v209
	v_add_f32_e32 v210, 1.0, v210
	v_add_f32_e32 v211, 1.0, v211
	v_rcp_f32_e32 v208, v208
	v_rcp_f32_e32 v209, v209
	v_rcp_f32_e32 v210, v210
	v_rcp_f32_e32 v211, v211
	s_nop 0
	v_pk_mul_f32 v[40:41], v[40:41], v[208:209]
	v_pk_mul_f32 v[42:43], v[42:43], v[210:211]
	v_cvt_pk_bf16_f32 v98, v40, v41
	v_cvt_pk_bf16_f32 v99, v42, v43
	global_store_dwordx4 v188, v[96:99], s[30:31]
	s_add_u32 s30, s30, 0x157c00
	s_addc_u32 s31, s31, 0
	ds_read_b128 v[166:169], v206 offset:64
	ds_read_b128 v[174:177], v206 offset:320
	ds_read_b128 v[170:173], v206 offset:192
	ds_read_b128 v[118:121], v206 offset:448
	s_waitcnt lgkmcnt(0)
; __device__ __forceinline__ unsigned cvt_pk_bf16(float lo, float hi) { unsigned r; asm volatile("v_cvt_pk_bf16_f32 %0, %1, %2" : "=v"(r) : "v"(lo), "v"(hi)); return r; }
;     __device__ __forceinline__ void operator()(const f32x4 (&acc)[2][2][4][2], const Unit& u, int wr, int wc, int fr, int fq) const {
;     ...
;                         for (int jj = 0; jj < 4; ++jj) {
;                             const float cur = acc[ai][bj][m][n][jj];
;                             float o1, o2;
;                             if (m > 0) { const float pv = acc[ai][bj][m > 0 ? m - 1 : 0][n][jj]; o1 = dppf<0x121>(0.f, pv); o2 = dppf<0x122>(0.f, pv); }
;                             else { o1 = h15[bj][jj]; o2 = (fr == 0) ? h14[bj][jj] : h15[bj][jj]; }
;                             const float p1 = dppf<0x111>(o1, cur), p2 = dppf<0x112>(o2, cur);
;                             val[bj][jj] = w2[bj][jj] * cur + w1[bj][jj] * p1 + w0[bj][jj] * p2 + bb[bj][jj];
;                         }
;                     float y[4];
; #pragma unroll
;                     for (int jj = 0; jj < 4; ++jj) { const float g = val[1][jj]; y[jj] = val[0][jj] * g * __builtin_amdgcn_rcpf(1.0f + __builtin_amdgcn_exp2f(-1.4426950408889634f * g)); }
;                     u32x2 w; w.x = cvt_pk_bf16(y[0], y[1]); w.y = cvt_pk_bf16(y[2], y[3]);
;                     if (n == 0) keep[ai][m] = w;
;                     else { const int row = u.pm * BM + ai * HALF + wr * 64 + m * 16 + fr;
;                         u32x4 w4; w4.x = keep[ai][m].x; w4.y = keep[ai][m].y; w4.z = w.x; w4.w = w.y;
;                         *(u32x4*)(act + (size_t)row * dff + ch0 - 4) = w4; }
	v_mov_b32_dpp v174, v8 row_shr:1 row_mask:0xf bank_mask:0xf
	v_mov_b32_dpp v175, v9 row_shr:1 row_mask:0xf bank_mask:0xf
	v_mov_b32_dpp v176, v10 row_shr:1 row_mask:0xf bank_mask:0xf
	v_mov_b32_dpp v177, v11 row_shr:1 row_mask:0xf bank_mask:0xf
	v_mov_b32_dpp v166, v12 row_shr:1 row_mask:0xf bank_mask:0xf
	v_mov_b32_dpp v167, v13 row_shr:1 row_mask:0xf bank_mask:0xf
	v_mov_b32_dpp v168, v14 row_shr:1 row_mask:0xf bank_mask:0xf
	v_mov_b32_dpp v169, v15 row_shr:1 row_mask:0xf bank_mask:0xf
	v_pk_fma_f32 v[8:9], v[142:143], v[8:9], v[150:151]
	v_pk_fma_f32 v[10:11], v[144:145], v[10:11], v[152:153]
	v_pk_fma_f32 v[8:9], v[134:135], v[12:13], v[8:9]
	v_pk_fma_f32 v[10:11], v[136:137], v[14:15], v[10:11]
	v_pk_fma_f32 v[8:9], v[126:127], v[20:21], v[8:9]
	v_pk_fma_f32 v[10:11], v[128:129], v[22:23], v[10:11]
	v_pk_fma_f32 v[12:13], v[142:143], v[12:13], v[150:151]
	v_pk_fma_f32 v[14:15], v[144:145], v[14:15], v[152:153]
	v_pk_fma_f32 v[12:13], v[134:135], v[20:21], v[12:13]
	v_pk_fma_f32 v[14:15], v[136:137], v[22:23], v[14:15]
	v_pk_fma_f32 v[12:13], v[126:127], v[28:29], v[12:13]
	v_pk_fma_f32 v[14:15], v[128:129], v[30:31], v[14:15]
	v_pk_fma_f32 v[20:21], v[142:143], v[20:21], v[150:151]
	v_pk_fma_f32 v[22:23], v[144:145], v[22:23], v[152:153]
	v_pk_fma_f32 v[20:21], v[134:135], v[28:29], v[20:21]
	v_pk_fma_f32 v[22:23], v[136:137], v[30:31], v[22:23]
	v_pk_fma_f32 v[20:21], v[126:127], v[174:175], v[20:21]
	v_pk_fma_f32 v[22:23], v[128:129], v[176:177], v[22:23]
	v_pk_fma_f32 v[28:29], v[142:143], v[28:29], v[150:151]
	v_pk_fma_f32 v[30:31], v[144:145], v[30:31], v[152:153]
	v_pk_fma_f32 v[28:29], v[134:135], v[174:175], v[28:29]
	v_pk_fma_f32 v[30:31], v[136:137], v[176:177], v[30:31]
	v_pk_fma_f32 v[28:29], v[126:127], v[166:167], v[28:29]
	v_pk_fma_f32 v[30:31], v[128:129], v[168:169], v[30:31]
	v_mov_b32_dpp v118, v0 row_shr:1 row_mask:0xf bank_mask:0xf
	v_mov_b32_dpp v119, v1 row_shr:1 row_mask:0xf bank_mask:0xf
	v_mov_b32_dpp v120, v2 row_shr:1 row_mask:0xf bank_mask:0xf
	v_mov_b32_dpp v121, v3 row_shr:1 row_mask:0xf bank_mask:0xf
	v_mov_b32_dpp v170, v4 row_shr:1 row_mask:0xf bank_mask:0xf
	v_mov_b32_dpp v171, v5 row_shr:1 row_mask:0xf bank_mask:0xf
	v_mov_b32_dpp v172, v6 row_shr:1 row_mask:0xf bank_mask:0xf
	v_mov_b32_dpp v173, v7 row_shr:1 row_mask:0xf bank_mask:0xf
	v_pk_fma_f32 v[0:1], v[146:147], v[0:1], v[154:155]
	v_pk_fma_f32 v[2:3], v[148:149], v[2:3], v[156:157]
	v_pk_fma_f32 v[0:1], v[138:139], v[4:5], v[0:1]
	v_pk_fma_f32 v[2:3], v[140:141], v[6:7], v[2:3]
	v_pk_fma_f32 v[0:1], v[130:131], v[16:17], v[0:1]
	v_pk_fma_f32 v[2:3], v[132:133], v[18:19], v[2:3]
	v_pk_fma_f32 v[4:5], v[146:147], v[4:5], v[154:155]
	v_pk_fma_f32 v[6:7], v[148:149], v[6:7], v[156:157]
	v_pk_fma_f32 v[4:5], v[138:139], v[16:17], v[4:5]
	v_pk_fma_f32 v[6:7], v[140:141], v[18:19], v[6:7]
	v_pk_fma_f32 v[4:5], v[130:131], v[24:25], v[4:5]
	v_pk_fma_f32 v[6:7], v[132:133], v[26:27], v[6:7]
	v_pk_fma_f32 v[16:17], v[146:147], v[16:17], v[154:155]
	v_pk_fma_f32 v[18:19], v[148:149], v[18:19], v[156:157]
	v_pk_fma_f32 v[16:17], v[138:139], v[24:25], v[16:17]
	v_pk_fma_f32 v[18:19], v[140:141], v[26:27], v[18:19]
	v_pk_fma_f32 v[16:17], v[130:131], v[118:119], v[16:17]
	v_pk_fma_f32 v[18:19], v[132:133], v[120:121], v[18:19]
	v_pk_fma_f32 v[24:25], v[146:147], v[24:25], v[154:155]
	v_pk_fma_f32 v[26:27], v[148:149], v[26:27], v[156:157]
	v_pk_fma_f32 v[24:25], v[138:139], v[118:119], v[24:25]
	v_pk_fma_f32 v[26:27], v[140:141], v[120:121], v[26:27]
	v_pk_fma_f32 v[24:25], v[130:131], v[170:171], v[24:25]
	v_pk_fma_f32 v[26:27], v[132:133], v[172:173], v[26:27]
	v_mul_f32_e32 v208, s71, v24
	v_mul_f32_e32 v209, s71, v25
	v_mul_f32_e32 v210, s71, v26
	v_mul_f32_e32 v211, s71, v27
	v_exp_f32_e32 v208, v208
	v_exp_f32_e32 v209, v209
	v_exp_f32_e32 v210, v210
	v_exp_f32_e32 v211, v211
	v_pk_mul_f32 v[28:29], v[28:29], v[24:25]
	v_pk_mul_f32 v[30:31], v[30:31], v[26:27]
	v_add_f32_e32 v208, 1.0, v208
	v_add_f32_e32 v209, 1.0, v209
	v_add_f32_e32 v210, 1.0, v210
	v_add_f32_e32 v211, 1.0, v211
	v_rcp_f32_e32 v208, v208
	v_rcp_f32_e32 v209, v209
	v_rcp_f32_e32 v210, v210
	v_rcp_f32_e32 v211, v211
	s_nop 0
	v_pk_mul_f32 v[28:29], v[28:29], v[208:209]
	v_pk_mul_f32 v[30:31], v[30:31], v[210:211]
	v_cvt_pk_bf16_f32 v90, v28, v29
	v_cvt_pk_bf16_f32 v91, v30, v31
	global_store_dwordx4 v188, v[88:91], s[30:31]
	s_add_u32 s30, s30, 0x2c00
	s_addc_u32 s31, s31, 0
	v_mul_f32_e32 v208, s71, v16
	v_mul_f32_e32 v209, s71, v17
	v_mul_f32_e32 v210, s71, v18
	v_mul_f32_e32 v211, s71, v19
	v_exp_f32_e32 v208, v208
	v_exp_f32_e32 v209, v209
	v_exp_f32_e32 v210, v210
	v_exp_f32_e32 v211, v211
	v_pk_mul_f32 v[20:21], v[20:21], v[16:17]
	v_pk_mul_f32 v[22:23], v[22:23], v[18:19]
	v_add_f32_e32 v208, 1.0, v208
	v_add_f32_e32 v209, 1.0, v209
	v_add_f32_e32 v210, 1.0, v210
	v_add_f32_e32 v211, 1.0, v211
	v_rcp_f32_e32 v208, v208
	v_rcp_f32_e32 v209, v209
	v_rcp_f32_e32 v210, v210
	v_rcp_f32_e32 v211, v211
	s_nop 0
	v_pk_mul_f32 v[20:21], v[20:21], v[208:209]
	v_pk_mul_f32 v[22:23], v[22:23], v[210:211]
	v_cvt_pk_bf16_f32 v82, v20, v21
	v_cvt_pk_bf16_f32 v83, v22, v23
	global_store_dwordx4 v188, v[80:83], s[30:31]
	s_add_u32 s30, s30, 0x2c00
	s_addc_u32 s31, s31, 0
	v_mul_f32_e32 v208, s71, v4
	v_mul_f32_e32 v209, s71, v5
	v_mul_f32_e32 v210, s71, v6
	v_mul_f32_e32 v211, s71, v7
	v_exp_f32_e32 v208, v208
	v_exp_f32_e32 v209, v209
	v_exp_f32_e32 v210, v210
	v_exp_f32_e32 v211, v211
	v_pk_mul_f32 v[12:13], v[12:13], v[4:5]
	v_pk_mul_f32 v[14:15], v[14:15], v[6:7]
	v_add_f32_e32 v208, 1.0, v208
	v_add_f32_e32 v209, 1.0, v209
	v_add_f32_e32 v210, 1.0, v210
	v_add_f32_e32 v211, 1.0, v211
	v_rcp_f32_e32 v208, v208
	v_rcp_f32_e32 v209, v209
	v_rcp_f32_e32 v210, v210
	v_rcp_f32_e32 v211, v211
	s_nop 0
	v_pk_mul_f32 v[12:13], v[12:13], v[208:209]
	v_pk_mul_f32 v[14:15], v[14:15], v[210:211]
	v_cvt_pk_bf16_f32 v70, v12, v13
	v_cvt_pk_bf16_f32 v71, v14, v15
	global_store_dwordx4 v188, v[68:71], s[30:31]
	s_add_u32 s30, s30, 0x2c00
	s_addc_u32 s31, s31, 0
	v_mul_f32_e32 v208, s71, v0
	v_mul_f32_e32 v209, s71, v1
	v_mul_f32_e32 v210, s71, v2
	v_mul_f32_e32 v211, s71, v3
	v_exp_f32_e32 v208, v208
	v_exp_f32_e32 v209, v209
	v_exp_f32_e32 v210, v210
	v_exp_f32_e32 v211, v211
	v_pk_mul_f32 v[8:9], v[8:9], v[0:1]
	v_pk_mul_f32 v[10:11], v[10:11], v[2:3]
	v_add_f32_e32 v208, 1.0, v208
	v_add_f32_e32 v209, 1.0, v209
	v_add_f32_e32 v210, 1.0, v210
	v_add_f32_e32 v211, 1.0, v211
	v_rcp_f32_e32 v208, v208
	v_rcp_f32_e32 v209, v209
	v_rcp_f32_e32 v210, v210
	v_rcp_f32_e32 v211, v211
	s_nop 0
	v_pk_mul_f32 v[8:9], v[8:9], v[208:209]
	v_pk_mul_f32 v[10:11], v[10:11], v[210:211]
	v_cvt_pk_bf16_f32 v66, v8, v9
	v_cvt_pk_bf16_f32 v67, v10, v11
	global_store_dwordx4 v188, v[64:67], s[30:31]
	s_not_b64 s[10:11], s[36:37]
	s_andn2_b64 vcc, exec, s[8:9]
	s_mov_b64 s[8:9], -1
	s_cbranch_vccnz .LBB0_400
	s_and_b64 vcc, exec, s[10:11]
	s_cbranch_vccnz .LBB0_399
	s_barrier
	s_branch .LBB0_399
